# GEMM K-loop: end-of-compute-segment s_barrier moved ahead of the last 2 MFMAs (raised to prio 2) so the partner half starts its MFMAs during the barrier hand-off
# speedup vs baseline: 1.0067x; 1.0067x over previous
; #define PG8_STAGE(bufoff, gbase, voff) do { _Pragma("unroll") for (int _i = 0; _i < 2; ++_i) \
;         __builtin_amdgcn_global_load_lds((const unsigned*)((const char*)(gbase) + (voff)[_i]), (PG8_LAS unsigned*)(lds + (bufoff) + ldsw + _i * 8192), 16, 0, 0); } while (0)
; #define PG8_LDA(dst, b, h) do { _Pragma("unroll") for (int m = 0; m < 4; ++m) _Pragma("unroll") for (int k = 0; k < 2; ++k) dst[m][k] = *(const PG8_LAS bf16x8*)(lds + PG8_SA(b, h) + aoff + m * 2048 + k * 1024); } while (0)
; #define PG8_LDB(dst, b, h) do { _Pragma("unroll") for (int n = 0; n < 2; ++n) _Pragma("unroll") for (int k = 0; k < 2; ++k) dst[n][k] = *(const PG8_LAS bf16x8*)(lds + PG8_SB(b, h) + boff + n * 2048 + k * 1024); } while (0)
; #define PG8_MMA(ai, bj, At, Bt) do { __builtin_amdgcn_s_setprio(1); _Pragma("unroll") for (int m = 0; m < 4; ++m) _Pragma("unroll") for (int n = 0; n < 2; ++n) _Pragma("unroll") for (int k = 0; k < 2; ++k) \
;         acc[ai][bj][m][n] = __builtin_amdgcn_mfma_f32_16x16x32_bf16(Bt[n][k], At[m][k], acc[ai][bj][m][n], 0, 0, 0); __builtin_amdgcn_s_setprio(0); } while (0)
; #define PG8_WAIT_V(n) asm volatile("s_waitcnt vmcnt(" #n ")" ::: "memory")
; #define PG8_WAIT_L(n) asm volatile("s_waitcnt lgkmcnt(" #n ")" ::: "memory")
; #define PG8_BAR __builtin_amdgcn_s_barrier()
; template <class Epi, class Sched, bool ALIGN_EPI = false, bool SP2 = false>
; __device__ __forceinline__ void gemm_phase(PG8_LAS unsigned char* lds, const Gemm g, const Sched& S, const Epi& E) {
;     ...
;         for (int t = 0; t < nt; t += 2) {
;             const bool last = (t == nt - 2);
;             const char* a1 = cA + (size_t)(t + 1) * kstepA;
;             const char* a2 = last ? nA : cA + (size_t)(t + 2) * kstepA; const char* b2 = last ? nB : cB + (size_t)(t + 2) * kstepB;
;             const char* a3 = a2 + kstepA; const char* b3 = b2 + kstepB;
;             if (last && has_next) { S.a_ready(nxt); E.prefetch(nxt, ui + 1, tid); }
;             if constexpr (SP2) {
;             PG8_LDB(B0, 0, 0); PG8_LDB(B1, 0, 1); PG8_SCHED; PG8_LDA(At, 0, 0); PG8_STAGE(PG8_SA(1, 1), a1 + hstepA, voffA);
;             PG8_WAIT_V(8); PG8_WAIT_L(0); PG8_BAR; PG8_MMA(0, 0, At, B0); PG8_MMA(0, 1, At, B1); PG8_BAR; PG8_SCHED;
;             PG8_LDA(At, 0, 1); PG8_STAGE(PG8_SB(0, 0), b2, voffB); PG8_STAGE(PG8_SB(0, 1), b2 + hstepB, voffB); PG8_STAGE(PG8_SA(0, 0), a2, voffA);
.LBB0_507:
	s_add_u32 s18, s14, 1
	s_addc_u32 s19, s15, 0
	s_lshl_b64 s[60:61], s[18:19], s48
	s_add_u32 s14, s14, 2
	s_addc_u32 s15, s15, 0
	s_lshl_b64 s[18:19], s[14:15], s48
	s_add_u32 s18, s2, s18
	s_addc_u32 s19, s3, s19
	s_and_b64 s[16:17], s[16:17], exec
	s_cselect_b32 s24, s52, s18
	s_cselect_b32 s25, s53, s19
	s_cselect_b32 s19, s55, s50
	s_cselect_b32 s18, s54, s39
	s_add_u32 s16, s24, s35
	s_addc_u32 s17, s25, 0
	s_add_u32 s20, s18, 0x8000
	s_addc_u32 s21, s19, 0
	s_add_i32 s51, 0, 0x10000
	s_add_i32 s72, 0, 0x14000
	v_add_u32_e32 v148, s51, v195
	v_add_u32_e32 v164, s72, v195
	s_waitcnt lgkmcnt(0)
	ds_read_b128 v[136:139], v148
	ds_read_b128 v[140:143], v148 offset:1024
	ds_read_b128 v[144:147], v148 offset:2048
	ds_read_b128 v[148:151], v148 offset:3072
	ds_read_b128 v[152:155], v164
	ds_read_b128 v[156:159], v164 offset:1024
	ds_read_b128 v[160:163], v164 offset:2048
	ds_read_b128 v[164:167], v164 offset:3072
	s_add_u32 s60, s31, s60
	s_addc_u32 s61, s36, s61
	v_lshl_add_u64 v[180:181], s[60:61], 0, v[184:185]
	s_add_i32 m0, s63, 0xc000
	ds_read_b128 v[168:171], v242
	ds_read_b128 v[172:175], v242 offset:1024
	ds_read_b128 v[176:179], v242 offset:2048
	ds_read_b128 v[200:203], v242 offset:3072
	ds_read_b128 v[204:207], v242 offset:4096
	ds_read_b128 v[208:211], v242 offset:5120
	ds_read_b128 v[212:215], v242 offset:6144
	ds_read_b128 v[244:247], v242 offset:7168
	global_load_lds_dwordx4 v[180:181], off
	v_lshl_add_u64 v[180:181], s[60:61], 0, v[188:189]
	s_add_i32 m0, s63, 0xe000
	s_nop 0
	global_load_lds_dwordx4 v[180:181], off
	s_waitcnt vmcnt(8)
	s_waitcnt lgkmcnt(0)
	s_barrier
	s_setprio 1
	s_waitcnt lgkmcnt(0)
	v_mfma_f32_16x16x32_bf16 v[126:129], v[136:139], v[168:171], v[126:129]
	v_mfma_f32_16x16x32_bf16 v[118:121], v[144:147], v[168:171], v[118:121]
	v_mfma_f32_16x16x32_bf16 v[110:113], v[136:139], v[176:179], v[110:113]
	v_mfma_f32_16x16x32_bf16 v[102:105], v[144:147], v[176:179], v[102:105]
	v_mfma_f32_16x16x32_bf16 v[94:97], v[136:139], v[204:207], v[94:97]
	v_mfma_f32_16x16x32_bf16 v[86:89], v[144:147], v[204:207], v[86:89]
	v_mfma_f32_16x16x32_bf16 v[78:81], v[136:139], v[212:215], v[78:81]
	v_mfma_f32_16x16x32_bf16 v[70:73], v[144:147], v[212:215], v[70:73]
	v_mfma_f32_16x16x32_bf16 v[126:129], v[140:143], v[172:175], v[126:129]
	v_mfma_f32_16x16x32_bf16 v[118:121], v[148:151], v[172:175], v[118:121]
	v_mfma_f32_16x16x32_bf16 v[110:113], v[140:143], v[200:203], v[110:113]
	v_mfma_f32_16x16x32_bf16 v[102:105], v[148:151], v[200:203], v[102:105]
	v_mfma_f32_16x16x32_bf16 v[94:97], v[140:143], v[208:211], v[94:97]
	v_mfma_f32_16x16x32_bf16 v[86:89], v[148:151], v[208:211], v[86:89]
	v_mfma_f32_16x16x32_bf16 v[78:81], v[140:143], v[244:247], v[78:81]
	v_mfma_f32_16x16x32_bf16 v[70:73], v[148:151], v[244:247], v[70:73]
	s_setprio 0
	s_setprio 1
	v_mfma_f32_16x16x32_bf16 v[122:125], v[152:155], v[168:171], v[122:125]
	v_mfma_f32_16x16x32_bf16 v[114:117], v[160:163], v[168:171], v[114:117]
	v_mfma_f32_16x16x32_bf16 v[106:109], v[152:155], v[176:179], v[106:109]
	v_mfma_f32_16x16x32_bf16 v[98:101], v[160:163], v[176:179], v[98:101]
	v_mfma_f32_16x16x32_bf16 v[90:93], v[152:155], v[204:207], v[90:93]
	v_mfma_f32_16x16x32_bf16 v[82:85], v[160:163], v[204:207], v[82:85]
	v_mfma_f32_16x16x32_bf16 v[74:77], v[152:155], v[212:215], v[74:77]
	v_mfma_f32_16x16x32_bf16 v[66:69], v[160:163], v[212:215], v[66:69]
	v_mfma_f32_16x16x32_bf16 v[122:125], v[156:159], v[172:175], v[122:125]
	v_mfma_f32_16x16x32_bf16 v[114:117], v[164:167], v[172:175], v[114:117]
	v_mfma_f32_16x16x32_bf16 v[106:109], v[156:159], v[200:203], v[106:109]
	v_mfma_f32_16x16x32_bf16 v[98:101], v[164:167], v[200:203], v[98:101]
	v_mfma_f32_16x16x32_bf16 v[90:93], v[156:159], v[208:211], v[90:93]
	v_mfma_f32_16x16x32_bf16 v[82:85], v[164:167], v[208:211], v[82:85]
	s_setprio 2
	s_barrier
	v_mfma_f32_16x16x32_bf16 v[74:77], v[156:159], v[244:247], v[74:77]
	v_mfma_f32_16x16x32_bf16 v[66:69], v[164:167], v[244:247], v[66:69]
	s_setprio 0
	s_add_i32 s51, s51, s62
	v_lshl_add_u64 v[180:181], s[18:19], 0, v[186:187]
	s_mov_b32 m0, s51
	ds_read_b128 v[168:171], v242 offset:16384
	ds_read_b128 v[172:175], v242 offset:17408
	ds_read_b128 v[176:179], v242 offset:18432
	ds_read_b128 v[200:203], v242 offset:19456
	ds_read_b128 v[204:207], v242 offset:20480
	ds_read_b128 v[208:211], v242 offset:21504
	ds_read_b128 v[212:215], v242 offset:22528
	ds_read_b128 v[244:247], v242 offset:23552
	global_load_lds_dwordx4 v[180:181], off
	s_add_i32 m0, s51, 0x2000
	s_add_u32 s60, s18, 0x4000
	v_lshl_add_u64 v[180:181], s[18:19], 0, v[190:191]
	s_addc_u32 s61, s19, 0
	s_add_i32 s51, s72, s62
	global_load_lds_dwordx4 v[180:181], off
	v_lshl_add_u64 v[180:181], s[60:61], 0, v[186:187]
	s_mov_b32 m0, s51
	s_nop 0
	global_load_lds_dwordx4 v[180:181], off
	v_lshl_add_u64 v[180:181], s[60:61], 0, v[190:191]
	s_add_i32 m0, s51, 0x2000
	s_nop 0
	global_load_lds_dwordx4 v[180:181], off
	v_lshl_add_u64 v[180:181], s[24:25], 0, v[184:185]
	s_mov_b32 m0, s63
	s_nop 0
	global_load_lds_dwordx4 v[180:181], off
	v_lshl_add_u64 v[180:181], s[24:25], 0, v[188:189]
	s_mov_b32 m0, s28
	s_nop 0
	global_load_lds_dwordx4 v[180:181], off
	s_waitcnt vmcnt(8)
	s_waitcnt lgkmcnt(0)
	s_barrier
; #define PG8_STAGE(bufoff, gbase, voff) do { _Pragma("unroll") for (int _i = 0; _i < 2; ++_i) \
;         __builtin_amdgcn_global_load_lds((const unsigned*)((const char*)(gbase) + (voff)[_i]), (PG8_LAS unsigned*)(lds + (bufoff) + ldsw + _i * 8192), 16, 0, 0); } while (0)
; #define PG8_LDA(dst, b, h) do { _Pragma("unroll") for (int m = 0; m < 4; ++m) _Pragma("unroll") for (int k = 0; k < 2; ++k) dst[m][k] = *(const PG8_LAS bf16x8*)(lds + PG8_SA(b, h) + aoff + m * 2048 + k * 1024); } while (0)
; #define PG8_LDB(dst, b, h) do { _Pragma("unroll") for (int n = 0; n < 2; ++n) _Pragma("unroll") for (int k = 0; k < 2; ++k) dst[n][k] = *(const PG8_LAS bf16x8*)(lds + PG8_SB(b, h) + boff + n * 2048 + k * 1024); } while (0)
; #define PG8_MMA(ai, bj, At, Bt) do { __builtin_amdgcn_s_setprio(1); _Pragma("unroll") for (int m = 0; m < 4; ++m) _Pragma("unroll") for (int n = 0; n < 2; ++n) _Pragma("unroll") for (int k = 0; k < 2; ++k) \
;         acc[ai][bj][m][n] = __builtin_amdgcn_mfma_f32_16x16x32_bf16(Bt[n][k], At[m][k], acc[ai][bj][m][n], 0, 0, 0); __builtin_amdgcn_s_setprio(0); } while (0)
; #define PG8_WAIT_V(n) asm volatile("s_waitcnt vmcnt(" #n ")" ::: "memory")
; #define PG8_WAIT_L(n) asm volatile("s_waitcnt lgkmcnt(" #n ")" ::: "memory")
; #define PG8_BAR __builtin_amdgcn_s_barrier()
; #define PG8_SCHED __builtin_amdgcn_sched_barrier(0)
; template <class Epi, class Sched, bool ALIGN_EPI = false, bool SP2 = false>
; __device__ __forceinline__ void gemm_phase(PG8_LAS unsigned char* lds, const Gemm g, const Sched& S, const Epi& E) {
;     ...
;             PG8_WAIT_V(8); PG8_WAIT_L(0); PG8_BAR; PG8_MMA(1, 0, At, B0); PG8_MMA(1, 1, At, B1); PG8_BAR; PG8_SCHED;
;             PG8_LDB(B0, 1, 0); PG8_LDB(B1, 1, 1); PG8_SCHED; PG8_LDA(At, 1, 0); PG8_STAGE(PG8_SA(0, 1), a2 + hstepA, voffA);
;             PG8_WAIT_V(8); PG8_WAIT_L(0); PG8_BAR; PG8_MMA(0, 0, At, B0); PG8_MMA(0, 1, At, B1); PG8_BAR; PG8_SCHED;
	s_setprio 1
	s_waitcnt lgkmcnt(0)
	v_mfma_f32_16x16x32_bf16 v[62:65], v[136:139], v[168:171], v[62:65]
	v_mfma_f32_16x16x32_bf16 v[54:57], v[144:147], v[168:171], v[54:57]
	v_mfma_f32_16x16x32_bf16 v[46:49], v[136:139], v[176:179], v[46:49]
	v_mfma_f32_16x16x32_bf16 v[38:41], v[144:147], v[176:179], v[38:41]
	v_mfma_f32_16x16x32_bf16 v[30:33], v[136:139], v[204:207], v[30:33]
	v_mfma_f32_16x16x32_bf16 v[22:25], v[144:147], v[204:207], v[22:25]
	v_mfma_f32_16x16x32_bf16 v[14:17], v[136:139], v[212:215], v[14:17]
	v_mfma_f32_16x16x32_bf16 v[6:9], v[144:147], v[212:215], v[6:9]
	v_mfma_f32_16x16x32_bf16 v[62:65], v[140:143], v[172:175], v[62:65]
	v_mfma_f32_16x16x32_bf16 v[54:57], v[148:151], v[172:175], v[54:57]
	v_mfma_f32_16x16x32_bf16 v[46:49], v[140:143], v[200:203], v[46:49]
	v_mfma_f32_16x16x32_bf16 v[38:41], v[148:151], v[200:203], v[38:41]
	v_mfma_f32_16x16x32_bf16 v[30:33], v[140:143], v[208:211], v[30:33]
	v_mfma_f32_16x16x32_bf16 v[22:25], v[148:151], v[208:211], v[22:25]
	v_mfma_f32_16x16x32_bf16 v[14:17], v[140:143], v[244:247], v[14:17]
	v_mfma_f32_16x16x32_bf16 v[6:9], v[148:151], v[244:247], v[6:9]
	s_setprio 0
	s_setprio 1
	v_mfma_f32_16x16x32_bf16 v[58:61], v[152:155], v[168:171], v[58:61]
	v_mfma_f32_16x16x32_bf16 v[50:53], v[160:163], v[168:171], v[50:53]
	v_mfma_f32_16x16x32_bf16 v[42:45], v[152:155], v[176:179], v[42:45]
	v_mfma_f32_16x16x32_bf16 v[34:37], v[160:163], v[176:179], v[34:37]
	v_mfma_f32_16x16x32_bf16 v[26:29], v[152:155], v[204:207], v[26:29]
	v_mfma_f32_16x16x32_bf16 v[18:21], v[160:163], v[204:207], v[18:21]
	v_mfma_f32_16x16x32_bf16 v[10:13], v[152:155], v[212:215], v[10:13]
	v_mfma_f32_16x16x32_bf16 v[2:5], v[160:163], v[212:215], v[2:5]
	v_mfma_f32_16x16x32_bf16 v[58:61], v[156:159], v[172:175], v[58:61]
	v_mfma_f32_16x16x32_bf16 v[50:53], v[164:167], v[172:175], v[50:53]
	v_mfma_f32_16x16x32_bf16 v[42:45], v[156:159], v[200:203], v[42:45]
	v_mfma_f32_16x16x32_bf16 v[34:37], v[164:167], v[200:203], v[34:37]
	v_mfma_f32_16x16x32_bf16 v[26:29], v[156:159], v[208:211], v[26:29]
	v_mfma_f32_16x16x32_bf16 v[18:21], v[164:167], v[208:211], v[18:21]
	s_setprio 2
	s_barrier
	v_mfma_f32_16x16x32_bf16 v[10:13], v[156:159], v[244:247], v[10:13]
	v_mfma_f32_16x16x32_bf16 v[2:5], v[164:167], v[244:247], v[2:5]
	s_setprio 0
	s_add_i32 s51, 0, 0x18000
	s_add_i32 s60, 0, 0x1c000
	v_add_u32_e32 v148, s51, v195
	v_add_u32_e32 v164, s60, v195
	ds_read_b128 v[136:139], v148
	ds_read_b128 v[140:143], v148 offset:1024
	ds_read_b128 v[144:147], v148 offset:2048
	ds_read_b128 v[148:151], v148 offset:3072
	ds_read_b128 v[152:155], v164
	ds_read_b128 v[156:159], v164 offset:1024
	ds_read_b128 v[160:163], v164 offset:2048
	ds_read_b128 v[164:167], v164 offset:3072
	s_add_u32 s24, s24, s45
	s_addc_u32 s25, s25, s44
	s_mov_b32 m0, s29
	v_lshl_add_u64 v[180:181], s[24:25], 0, v[184:185]
	ds_read_b128 v[168:171], v242 offset:32768
	ds_read_b128 v[172:175], v242 offset:33792
	ds_read_b128 v[176:179], v242 offset:34816
	ds_read_b128 v[200:203], v242 offset:35840
	ds_read_b128 v[204:207], v242 offset:36864
	ds_read_b128 v[208:211], v242 offset:37888
	ds_read_b128 v[212:215], v242 offset:38912
	ds_read_b128 v[244:247], v242 offset:39936
	global_load_lds_dwordx4 v[180:181], off
	v_lshl_add_u64 v[180:181], s[24:25], 0, v[188:189]
	s_mov_b32 m0, s26
	s_nop 0
	global_load_lds_dwordx4 v[180:181], off
	s_waitcnt vmcnt(8)
	s_waitcnt lgkmcnt(0)
	s_barrier
	s_setprio 1
	s_waitcnt lgkmcnt(0)
	v_mfma_f32_16x16x32_bf16 v[126:129], v[136:139], v[168:171], v[126:129]
	v_mfma_f32_16x16x32_bf16 v[118:121], v[144:147], v[168:171], v[118:121]
	v_mfma_f32_16x16x32_bf16 v[110:113], v[136:139], v[176:179], v[110:113]
	v_mfma_f32_16x16x32_bf16 v[102:105], v[144:147], v[176:179], v[102:105]
	v_mfma_f32_16x16x32_bf16 v[94:97], v[136:139], v[204:207], v[94:97]
	v_mfma_f32_16x16x32_bf16 v[86:89], v[144:147], v[204:207], v[86:89]
	v_mfma_f32_16x16x32_bf16 v[78:81], v[136:139], v[212:215], v[78:81]
	v_mfma_f32_16x16x32_bf16 v[70:73], v[144:147], v[212:215], v[70:73]
	v_mfma_f32_16x16x32_bf16 v[126:129], v[140:143], v[172:175], v[126:129]
	v_mfma_f32_16x16x32_bf16 v[118:121], v[148:151], v[172:175], v[118:121]
	v_mfma_f32_16x16x32_bf16 v[110:113], v[140:143], v[200:203], v[110:113]
	v_mfma_f32_16x16x32_bf16 v[102:105], v[148:151], v[200:203], v[102:105]
	v_mfma_f32_16x16x32_bf16 v[94:97], v[140:143], v[208:211], v[94:97]
	v_mfma_f32_16x16x32_bf16 v[86:89], v[148:151], v[208:211], v[86:89]
	v_mfma_f32_16x16x32_bf16 v[78:81], v[140:143], v[244:247], v[78:81]
	v_mfma_f32_16x16x32_bf16 v[70:73], v[148:151], v[244:247], v[70:73]
	s_setprio 0
	s_setprio 1
	v_mfma_f32_16x16x32_bf16 v[122:125], v[152:155], v[168:171], v[122:125]
	v_mfma_f32_16x16x32_bf16 v[114:117], v[160:163], v[168:171], v[114:117]
	v_mfma_f32_16x16x32_bf16 v[106:109], v[152:155], v[176:179], v[106:109]
	v_mfma_f32_16x16x32_bf16 v[98:101], v[160:163], v[176:179], v[98:101]
	v_mfma_f32_16x16x32_bf16 v[90:93], v[152:155], v[204:207], v[90:93]
	v_mfma_f32_16x16x32_bf16 v[82:85], v[160:163], v[204:207], v[82:85]
	v_mfma_f32_16x16x32_bf16 v[74:77], v[152:155], v[212:215], v[74:77]
	v_mfma_f32_16x16x32_bf16 v[66:69], v[160:163], v[212:215], v[66:69]
	v_mfma_f32_16x16x32_bf16 v[122:125], v[156:159], v[172:175], v[122:125]
	v_mfma_f32_16x16x32_bf16 v[114:117], v[164:167], v[172:175], v[114:117]
	v_mfma_f32_16x16x32_bf16 v[106:109], v[156:159], v[200:203], v[106:109]
	v_mfma_f32_16x16x32_bf16 v[98:101], v[164:167], v[200:203], v[98:101]
	v_mfma_f32_16x16x32_bf16 v[90:93], v[156:159], v[208:211], v[90:93]
	v_mfma_f32_16x16x32_bf16 v[82:85], v[164:167], v[208:211], v[82:85]
	s_setprio 2
	s_barrier
; #define PG8_STAGE(bufoff, gbase, voff) do { _Pragma("unroll") for (int _i = 0; _i < 2; ++_i) \
;         __builtin_amdgcn_global_load_lds((const unsigned*)((const char*)(gbase) + (voff)[_i]), (PG8_LAS unsigned*)(lds + (bufoff) + ldsw + _i * 8192), 16, 0, 0); } while (0)
; #define PG8_LDA(dst, b, h) do { _Pragma("unroll") for (int m = 0; m < 4; ++m) _Pragma("unroll") for (int k = 0; k < 2; ++k) dst[m][k] = *(const PG8_LAS bf16x8*)(lds + PG8_SA(b, h) + aoff + m * 2048 + k * 1024); } while (0)
; #define PG8_MMA(ai, bj, At, Bt) do { __builtin_amdgcn_s_setprio(1); _Pragma("unroll") for (int m = 0; m < 4; ++m) _Pragma("unroll") for (int n = 0; n < 2; ++n) _Pragma("unroll") for (int k = 0; k < 2; ++k) \
;         acc[ai][bj][m][n] = __builtin_amdgcn_mfma_f32_16x16x32_bf16(Bt[n][k], At[m][k], acc[ai][bj][m][n], 0, 0, 0); __builtin_amdgcn_s_setprio(0); } while (0)
; #define PG8_WAIT_V(n) asm volatile("s_waitcnt vmcnt(" #n ")" ::: "memory")
; #define PG8_WAIT_L(n) asm volatile("s_waitcnt lgkmcnt(" #n ")" ::: "memory")
; #define PG8_BAR __builtin_amdgcn_s_barrier()
; #define PG8_SCHED __builtin_amdgcn_sched_barrier(0)
; template <class Epi, class Sched, bool ALIGN_EPI = false, bool SP2 = false>
; __device__ __forceinline__ void gemm_phase(PG8_LAS unsigned char* lds, const Gemm g, const Sched& S, const Epi& E) {
;     ...
;             PG8_WAIT_V(8); PG8_WAIT_L(0); PG8_BAR; PG8_MMA(0, 0, At, B0); PG8_MMA(0, 1, At, B1); PG8_BAR; PG8_SCHED;
;             PG8_LDA(At, 1, 1); PG8_STAGE(PG8_SB(1, 0), b3, voffB); PG8_STAGE(PG8_SB(1, 1), b3 + hstepB, voffB); PG8_STAGE(PG8_SA(1, 0), a3, voffA);
;             PG8_WAIT_V(8); PG8_WAIT_L(0); PG8_BAR; PG8_MMA(1, 0, At, B0); PG8_MMA(1, 1, At, B1); PG8_BAR; PG8_SCHED;
	v_mfma_f32_16x16x32_bf16 v[74:77], v[156:159], v[244:247], v[74:77]
	v_mfma_f32_16x16x32_bf16 v[66:69], v[164:167], v[244:247], v[66:69]
	s_setprio 0
	s_add_i32 s24, s51, s62
	v_lshl_add_u64 v[180:181], s[20:21], 0, v[186:187]
	s_mov_b32 m0, s24
	ds_read_b128 v[168:171], v242 offset:49152
	ds_read_b128 v[172:175], v242 offset:50176
	ds_read_b128 v[176:179], v242 offset:51200
	ds_read_b128 v[200:203], v242 offset:52224
	ds_read_b128 v[204:207], v242 offset:53248
	ds_read_b128 v[208:211], v242 offset:54272
	ds_read_b128 v[212:215], v242 offset:55296
	ds_read_b128 v[244:247], v242 offset:56320
	global_load_lds_dwordx4 v[180:181], off
	s_add_i32 m0, s24, 0x2000
	s_add_u32 s18, s18, 0xc000
	v_lshl_add_u64 v[180:181], s[20:21], 0, v[190:191]
	s_addc_u32 s19, s19, 0
	s_add_i32 s20, s60, s62
	global_load_lds_dwordx4 v[180:181], off
	v_lshl_add_u64 v[180:181], s[18:19], 0, v[186:187]
	s_mov_b32 m0, s20
	s_nop 0
	global_load_lds_dwordx4 v[180:181], off
	v_lshl_add_u64 v[180:181], s[18:19], 0, v[190:191]
	s_add_i32 m0, s20, 0x2000
	s_nop 0
	global_load_lds_dwordx4 v[180:181], off
	v_lshl_add_u64 v[180:181], s[16:17], 0, v[184:185]
	s_mov_b32 m0, s1
	s_nop 0
	global_load_lds_dwordx4 v[180:181], off
	v_lshl_add_u64 v[180:181], s[16:17], 0, v[188:189]
	s_mov_b32 m0, s0
	s_nop 0
	global_load_lds_dwordx4 v[180:181], off
	s_waitcnt vmcnt(8)
	s_waitcnt lgkmcnt(0)
	s_barrier
	s_setprio 1
	s_waitcnt lgkmcnt(0)
	v_mfma_f32_16x16x32_bf16 v[62:65], v[136:139], v[168:171], v[62:65]
	v_mfma_f32_16x16x32_bf16 v[54:57], v[144:147], v[168:171], v[54:57]
	v_mfma_f32_16x16x32_bf16 v[46:49], v[136:139], v[176:179], v[46:49]
	v_mfma_f32_16x16x32_bf16 v[38:41], v[144:147], v[176:179], v[38:41]
	v_mfma_f32_16x16x32_bf16 v[30:33], v[136:139], v[204:207], v[30:33]
	v_mfma_f32_16x16x32_bf16 v[22:25], v[144:147], v[204:207], v[22:25]
	v_mfma_f32_16x16x32_bf16 v[14:17], v[136:139], v[212:215], v[14:17]
	v_mfma_f32_16x16x32_bf16 v[6:9], v[144:147], v[212:215], v[6:9]
	v_mfma_f32_16x16x32_bf16 v[62:65], v[140:143], v[172:175], v[62:65]
	v_mfma_f32_16x16x32_bf16 v[54:57], v[148:151], v[172:175], v[54:57]
	v_mfma_f32_16x16x32_bf16 v[46:49], v[140:143], v[200:203], v[46:49]
	v_mfma_f32_16x16x32_bf16 v[38:41], v[148:151], v[200:203], v[38:41]
	v_mfma_f32_16x16x32_bf16 v[30:33], v[140:143], v[208:211], v[30:33]
	v_mfma_f32_16x16x32_bf16 v[22:25], v[148:151], v[208:211], v[22:25]
	v_mfma_f32_16x16x32_bf16 v[14:17], v[140:143], v[244:247], v[14:17]
	v_mfma_f32_16x16x32_bf16 v[6:9], v[148:151], v[244:247], v[6:9]
	s_setprio 0
	s_setprio 1
	v_mfma_f32_16x16x32_bf16 v[58:61], v[152:155], v[168:171], v[58:61]
	v_mfma_f32_16x16x32_bf16 v[50:53], v[160:163], v[168:171], v[50:53]
	v_mfma_f32_16x16x32_bf16 v[42:45], v[152:155], v[176:179], v[42:45]
	v_mfma_f32_16x16x32_bf16 v[34:37], v[160:163], v[176:179], v[34:37]
	v_mfma_f32_16x16x32_bf16 v[26:29], v[152:155], v[204:207], v[26:29]
	v_mfma_f32_16x16x32_bf16 v[18:21], v[160:163], v[204:207], v[18:21]
	v_mfma_f32_16x16x32_bf16 v[10:13], v[152:155], v[212:215], v[10:13]
	v_mfma_f32_16x16x32_bf16 v[2:5], v[160:163], v[212:215], v[2:5]
	v_mfma_f32_16x16x32_bf16 v[58:61], v[156:159], v[172:175], v[58:61]
	v_mfma_f32_16x16x32_bf16 v[50:53], v[164:167], v[172:175], v[50:53]
	v_mfma_f32_16x16x32_bf16 v[42:45], v[156:159], v[200:203], v[42:45]
	v_mfma_f32_16x16x32_bf16 v[34:37], v[164:167], v[200:203], v[34:37]
	v_mfma_f32_16x16x32_bf16 v[26:29], v[156:159], v[208:211], v[26:29]
	v_mfma_f32_16x16x32_bf16 v[18:21], v[164:167], v[208:211], v[18:21]
	s_setprio 2
	s_barrier
	v_mfma_f32_16x16x32_bf16 v[10:13], v[156:159], v[244:247], v[10:13]
	v_mfma_f32_16x16x32_bf16 v[2:5], v[164:167], v[244:247], v[2:5]
	s_setprio 0
	s_add_u32 s39, s39, 0x10000
	s_addc_u32 s50, s50, 0
	s_cmp_ge_u32 s14, s34
	s_cbranch_scc1 .LBB0_518
